# forgetting-attention QK: key fragments for the second sub-tile read from LDS six deep instead of one per MFMA
# baseline (speedup 1.0000x reference)
; #define LAS __attribute__((address_space(3)))
; __device__ __forceinline__ int crow(int r, int hi) { return (r & 3) + 8 * (r >> 2) + 4 * hi; }
; template <int TYPE> ...
;     ...
;     if (TYPE == 0) {
;         const float cb = cq - m;
; #pragma unroll
;         for (int g = 0; g < 4; ++g) {
;             const f32x4 c0 = *(const LAS f32x4*)(ckv + 8 * g + 4 * hi), c1 = *(const LAS f32x4*)(ckv + 32 + 8 * g + 4 * hi);
; #pragma unroll
;             for (int e = 0; e < 4; ++e) { p0[4 * g + e] = cb - c0[e]; p1[4 * g + e] = cb - c1[e]; }
;         }
;     } else {
; #pragma unroll
;         for (int r = 0; r < 16; ++r) { const int d0 = qpos - (kv0 + crow(r, hi)); p0[r] = biasT[d0 & 127] - m; p1[r] = biasT[(d0 - 32) & 127] - m; }
;     }
;     const LAS unsigned char* kp = Kt + r32 * KROW + 16 * hi;
; #pragma unroll
;     for (int d0 = 0; d0 < 4; ++d0) {
;         const bf16x8 a0 = *(const LAS bf16x8*)(kp + 32 * d0), a1 = *(const LAS bf16x8*)(kp + 32 * KROW + 32 * d0);
;         p0 = __builtin_amdgcn_mfma_f32_32x32x16_bf16(a0, qr[d0], p0, 0, 0, 0);
;         p1 = __builtin_amdgcn_mfma_f32_32x32x16_bf16(a1, qr[d0], p1, 0, 0, 0);
;     }
;     if (TYPE == 0) {
;         if (domask) {
; #pragma unroll
;             for (int r = 0; r < 16; ++r) { const int kv = kv0 + crow(r, hi); if (kv > qpos) p0[r] = NEGBIG; if (kv + 32 > qpos) p1[r] = NEGBIG; }
;         }
.LBB0_331:
	v_lshl_add_u32 v62, v102, 2, s4
	ds_read_b128 v[34:37], v62 offset:35840
	ds_read_b128 v[38:41], v62 offset:35872
	ds_read_b128 v[42:45], v62 offset:35904
	ds_read_b128 v[46:49], v62 offset:35936
	ds_read_b128 v[50:53], v62 offset:35968
	ds_read_b128 v[54:57], v62 offset:36000
	ds_read_b128 v[58:61], v62 offset:36032
	ds_read_b128 v[62:65], v62 offset:36064
	ds_read_b128 v[154:157], v153
	ds_read_b128 v[158:161], v153 offset:4608
	v_sub_f32_e32 v0, v119, v151
	s_waitcnt lgkmcnt(6)
	v_sub_f32_e32 v49, v0, v49
	v_sub_f32_e32 v48, v0, v48
	v_sub_f32_e32 v47, v0, v47
	v_sub_f32_e32 v46, v0, v46
	v_sub_f32_e32 v45, v0, v45
	v_sub_f32_e32 v44, v0, v44
	v_sub_f32_e32 v43, v0, v43
	v_sub_f32_e32 v42, v0, v42
	v_sub_f32_e32 v41, v0, v41
	v_sub_f32_e32 v40, v0, v40
	v_sub_f32_e32 v39, v0, v39
	v_sub_f32_e32 v38, v0, v38
	v_sub_f32_e32 v37, v0, v37
	v_sub_f32_e32 v36, v0, v36
	v_sub_f32_e32 v35, v0, v35
	v_sub_f32_e32 v34, v0, v34
	s_waitcnt lgkmcnt(2)
	v_sub_f32_e32 v65, v0, v65
	v_sub_f32_e32 v64, v0, v64
	s_waitcnt lgkmcnt(1)
	v_mfma_f32_32x32x16_bf16 v[34:49], v[154:157], v[66:69], v[34:49]
	ds_read_b128 v[154:157], v153 offset:32
	ds_read_b128 v[166:169], v153 offset:4640
	ds_read_b128 v[170:173], v153 offset:64
	ds_read_b128 v[174:177], v153 offset:4672
	ds_read_b128 v[178:181], v153 offset:96
	ds_read_b128 v[182:185], v153 offset:4704
	v_sub_f32_e32 v63, v0, v63
	v_sub_f32_e32 v62, v0, v62
	v_sub_f32_e32 v61, v0, v61
	v_sub_f32_e32 v60, v0, v60
	v_sub_f32_e32 v59, v0, v59
	v_sub_f32_e32 v58, v0, v58
	v_sub_f32_e32 v57, v0, v57
	v_sub_f32_e32 v56, v0, v56
	v_sub_f32_e32 v55, v0, v55
	v_sub_f32_e32 v54, v0, v54
	v_sub_f32_e32 v53, v0, v53
	v_sub_f32_e32 v52, v0, v52
	v_sub_f32_e32 v51, v0, v51
	v_sub_f32_e32 v50, v0, v50
	s_waitcnt lgkmcnt(5)
	v_mfma_f32_32x32x16_bf16 v[34:49], v[154:157], v[70:73], v[34:49]
	s_add_i32 s1, s49, 0xbf
	s_cmp_le_i32 s1, s66
	v_mfma_f32_32x32x16_bf16 v[50:65], v[158:161], v[66:69], v[50:65]
	s_waitcnt lgkmcnt(4)
	v_mfma_f32_32x32x16_bf16 v[50:65], v[166:169], v[70:73], v[50:65]
	s_waitcnt lgkmcnt(3)
	v_mfma_f32_32x32x16_bf16 v[34:49], v[170:173], v[74:77], v[34:49]
	s_waitcnt lgkmcnt(2)
	v_mfma_f32_32x32x16_bf16 v[50:65], v[174:177], v[74:77], v[50:65]
	s_waitcnt lgkmcnt(1)
	v_mfma_f32_32x32x16_bf16 v[34:49], v[178:181], v[78:81], v[34:49]
	s_waitcnt lgkmcnt(0)
	v_mfma_f32_32x32x16_bf16 v[50:65], v[182:185], v[78:81], v[50:65]
	s_cbranch_scc1 .LBB0_333
	v_add_u32_e32 v0, s49, v102
	v_add_u32_e32 v154, 0xa0, v0
	v_add_u32_e32 v153, 0x80, v0
	v_cmp_le_i32_e32 vcc, v154, v136
	s_nop 6
	v_cndmask_b32_e32 v50, v238, v50, vcc
	v_cmp_lt_i32_e32 vcc, v153, v136
	s_nop 1
	v_cndmask_b32_e32 v35, v238, v35, vcc
	v_cmp_le_i32_e32 vcc, v153, v136
	v_add_u32_e32 v153, 0xa1, v0
	s_nop 0
	v_cndmask_b32_e32 v34, v238, v34, vcc
	v_cmp_le_i32_e32 vcc, v153, v136
	v_add_u32_e32 v153, 0x82, v0
	s_nop 0
	v_cndmask_b32_e32 v51, v238, v51, vcc
	v_cmp_le_i32_e32 vcc, v153, v136
	v_add_u32_e32 v153, 0xa2, v0
	s_nop 0
	v_cndmask_b32_e32 v36, v238, v36, vcc
	v_cmp_le_i32_e32 vcc, v153, v136
	v_add_u32_e32 v153, 0x83, v0
	s_nop 0
	v_cndmask_b32_e32 v52, v238, v52, vcc
	v_cmp_le_i32_e32 vcc, v153, v136
	v_add_u32_e32 v153, 0xa3, v0
	s_nop 0
	v_cndmask_b32_e32 v37, v238, v37, vcc
	v_cmp_le_i32_e32 vcc, v153, v136
	v_add_u32_e32 v153, 0x88, v0
	s_nop 0
	v_cndmask_b32_e32 v53, v238, v53, vcc
	v_cmp_le_i32_e32 vcc, v153, v136
	v_add_u32_e32 v153, 0xa8, v0
	s_nop 0
	v_cndmask_b32_e32 v38, v238, v38, vcc
	v_cmp_le_i32_e32 vcc, v153, v136
	v_add_u32_e32 v153, 0x89, v0
	s_nop 0
	v_cndmask_b32_e32 v54, v238, v54, vcc
	v_cmp_le_i32_e32 vcc, v153, v136
	v_add_u32_e32 v153, 0xa9, v0
	s_nop 0
	v_cndmask_b32_e32 v39, v238, v39, vcc
	v_cmp_le_i32_e32 vcc, v153, v136
	v_add_u32_e32 v153, 0x8a, v0
	s_nop 0
	v_cndmask_b32_e32 v55, v238, v55, vcc
	v_cmp_le_i32_e32 vcc, v153, v136
	v_add_u32_e32 v153, 0xaa, v0
	s_nop 0
	v_cndmask_b32_e32 v40, v238, v40, vcc
	v_cmp_le_i32_e32 vcc, v153, v136
	v_add_u32_e32 v153, 0x8b, v0
	s_nop 0
	v_cndmask_b32_e32 v56, v238, v56, vcc
	v_cmp_le_i32_e32 vcc, v153, v136
	v_add_u32_e32 v153, 0xab, v0
	s_nop 0
	v_cndmask_b32_e32 v41, v238, v41, vcc
	v_cmp_le_i32_e32 vcc, v153, v136
	v_add_u32_e32 v153, 0x90, v0
	s_nop 0
	v_cndmask_b32_e32 v57, v238, v57, vcc
	v_cmp_le_i32_e32 vcc, v153, v136
	v_add_u32_e32 v153, 0xb0, v0
	s_nop 0
	v_cndmask_b32_e32 v42, v238, v42, vcc
	v_cmp_le_i32_e32 vcc, v153, v136
	v_add_u32_e32 v153, 0x91, v0
	s_nop 0
	v_cndmask_b32_e32 v58, v238, v58, vcc
	v_cmp_le_i32_e32 vcc, v153, v136
	v_add_u32_e32 v153, 0xb1, v0
	s_nop 0
	v_cndmask_b32_e32 v43, v238, v43, vcc
	v_cmp_le_i32_e32 vcc, v153, v136
	v_add_u32_e32 v153, 0x92, v0
	s_nop 0
	v_cndmask_b32_e32 v59, v238, v59, vcc
	v_cmp_le_i32_e32 vcc, v153, v136
	v_add_u32_e32 v153, 0xb2, v0
	s_nop 0
	v_cndmask_b32_e32 v44, v238, v44, vcc
	v_cmp_le_i32_e32 vcc, v153, v136
	v_add_u32_e32 v153, 0x93, v0
	s_nop 0
	v_cndmask_b32_e32 v60, v238, v60, vcc
	v_cmp_le_i32_e32 vcc, v153, v136
	v_add_u32_e32 v153, 0xb3, v0
	s_nop 0
	v_cndmask_b32_e32 v45, v238, v45, vcc
	v_cmp_le_i32_e32 vcc, v153, v136
	v_add_u32_e32 v153, 0x98, v0
	s_nop 0
	v_cndmask_b32_e32 v61, v238, v61, vcc
	v_cmp_le_i32_e32 vcc, v153, v136
	v_add_u32_e32 v153, 0xb8, v0
	s_nop 0
	v_cndmask_b32_e32 v46, v238, v46, vcc
	v_cmp_le_i32_e32 vcc, v153, v136
	v_add_u32_e32 v153, 0x99, v0
	s_nop 0
	v_cndmask_b32_e32 v62, v238, v62, vcc
	v_cmp_le_i32_e32 vcc, v153, v136
	v_add_u32_e32 v153, 0xb9, v0
	s_nop 0
	v_cndmask_b32_e32 v47, v238, v47, vcc
	v_cmp_le_i32_e32 vcc, v153, v136
	v_add_u32_e32 v153, 0x9a, v0
	s_nop 0
	v_cndmask_b32_e32 v63, v238, v63, vcc
	v_cmp_le_i32_e32 vcc, v153, v136
	v_add_u32_e32 v153, 0xba, v0
	s_nop 0
	v_cndmask_b32_e32 v48, v238, v48, vcc
	v_cmp_le_i32_e32 vcc, v153, v136
	v_add_u32_e32 v153, 0x9b, v0
	v_add_u32_e32 v0, 0xbb, v0
	v_cndmask_b32_e32 v64, v238, v64, vcc
	v_cmp_le_i32_e32 vcc, v153, v136
	s_nop 1
	v_cndmask_b32_e32 v49, v238, v49, vcc
	v_cmp_le_i32_e32 vcc, v0, v136
	s_nop 1
	v_cndmask_b32_e32 v65, v238, v65, vcc

; #define LAS __attribute__((address_space(3)))
; __device__ __forceinline__ int crow(int r, int hi) { return (r & 3) + 8 * (r >> 2) + 4 * hi; }
; template <int TYPE> ...
;     ...
;     if (TYPE == 0) {
;         const float cb = cq - m;
; #pragma unroll
;         for (int g = 0; g < 4; ++g) {
;             const f32x4 c0 = *(const LAS f32x4*)(ckv + 8 * g + 4 * hi), c1 = *(const LAS f32x4*)(ckv + 32 + 8 * g + 4 * hi);
; #pragma unroll
;             for (int e = 0; e < 4; ++e) { p0[4 * g + e] = cb - c0[e]; p1[4 * g + e] = cb - c1[e]; }
;         }
;     } else {
; #pragma unroll
;         for (int r = 0; r < 16; ++r) { const int d0 = qpos - (kv0 + crow(r, hi)); p0[r] = biasT[d0 & 127] - m; p1[r] = biasT[(d0 - 32) & 127] - m; }
;     }
;     const LAS unsigned char* kp = Kt + r32 * KROW + 16 * hi;
; #pragma unroll
;     for (int d0 = 0; d0 < 4; ++d0) {
;         const bf16x8 a0 = *(const LAS bf16x8*)(kp + 32 * d0), a1 = *(const LAS bf16x8*)(kp + 32 * KROW + 32 * d0);
;         p0 = __builtin_amdgcn_mfma_f32_32x32x16_bf16(a0, qr[d0], p0, 0, 0, 0);
;         p1 = __builtin_amdgcn_mfma_f32_32x32x16_bf16(a1, qr[d0], p1, 0, 0, 0);
;     }
;     if (TYPE == 0) {
;         if (domask) {
; #pragma unroll
;             for (int r = 0; r < 16; ++r) { const int kv = kv0 + crow(r, hi); if (kv > qpos) p0[r] = NEGBIG; if (kv + 32 > qpos) p1[r] = NEGBIG; }
;         }
.LBB0_358:
	v_lshl_add_u32 v62, v102, 2, s4
	ds_read_b128 v[34:37], v62 offset:35840
	ds_read_b128 v[38:41], v62 offset:35872
	ds_read_b128 v[42:45], v62 offset:35904
	ds_read_b128 v[46:49], v62 offset:35936
	ds_read_b128 v[50:53], v62 offset:35968
	ds_read_b128 v[54:57], v62 offset:36000
	ds_read_b128 v[58:61], v62 offset:36032
	ds_read_b128 v[62:65], v62 offset:36064
	ds_read_b128 v[142:145], v132
	ds_read_b128 v[148:151], v132 offset:4608
	v_sub_f32_e32 v0, v119, v130
	s_waitcnt lgkmcnt(6)
	v_sub_f32_e32 v49, v0, v49
	v_sub_f32_e32 v48, v0, v48
	v_sub_f32_e32 v47, v0, v47
	v_sub_f32_e32 v46, v0, v46
	v_sub_f32_e32 v45, v0, v45
	v_sub_f32_e32 v44, v0, v44
	v_sub_f32_e32 v43, v0, v43
	v_sub_f32_e32 v42, v0, v42
	v_sub_f32_e32 v41, v0, v41
	v_sub_f32_e32 v40, v0, v40
	v_sub_f32_e32 v39, v0, v39
	v_sub_f32_e32 v38, v0, v38
	v_sub_f32_e32 v37, v0, v37
	v_sub_f32_e32 v36, v0, v36
	v_sub_f32_e32 v35, v0, v35
	v_sub_f32_e32 v34, v0, v34
	s_waitcnt lgkmcnt(2)
	v_sub_f32_e32 v65, v0, v65
	v_sub_f32_e32 v64, v0, v64
	s_waitcnt lgkmcnt(1)
	v_mfma_f32_32x32x16_bf16 v[34:49], v[142:145], v[66:69], v[34:49]
	ds_read_b128 v[142:145], v132 offset:32
	ds_read_b128 v[166:169], v132 offset:4640
	ds_read_b128 v[170:173], v132 offset:64
	ds_read_b128 v[174:177], v132 offset:4672
	ds_read_b128 v[178:181], v132 offset:96
	ds_read_b128 v[182:185], v132 offset:4704
	v_sub_f32_e32 v63, v0, v63
	v_sub_f32_e32 v62, v0, v62
	v_sub_f32_e32 v61, v0, v61
	v_sub_f32_e32 v60, v0, v60
	v_sub_f32_e32 v59, v0, v59
	v_sub_f32_e32 v58, v0, v58
	v_sub_f32_e32 v57, v0, v57
	v_sub_f32_e32 v56, v0, v56
	v_sub_f32_e32 v55, v0, v55
	v_sub_f32_e32 v54, v0, v54
	v_sub_f32_e32 v53, v0, v53
	v_sub_f32_e32 v52, v0, v52
	v_sub_f32_e32 v51, v0, v51
	v_sub_f32_e32 v50, v0, v50
	s_waitcnt lgkmcnt(5)
	v_mfma_f32_32x32x16_bf16 v[34:49], v[142:145], v[70:73], v[34:49]
	s_add_i32 s1, s35, 0xbf
	s_cmp_le_i32 s1, s36
	v_mfma_f32_32x32x16_bf16 v[50:65], v[148:151], v[66:69], v[50:65]
	s_waitcnt lgkmcnt(4)
	v_mfma_f32_32x32x16_bf16 v[50:65], v[166:169], v[70:73], v[50:65]
	s_waitcnt lgkmcnt(3)
	v_mfma_f32_32x32x16_bf16 v[34:49], v[170:173], v[74:77], v[34:49]
	s_waitcnt lgkmcnt(2)
	v_mfma_f32_32x32x16_bf16 v[50:65], v[174:177], v[74:77], v[50:65]
	s_waitcnt lgkmcnt(1)
	v_mfma_f32_32x32x16_bf16 v[34:49], v[178:181], v[78:81], v[34:49]
	s_waitcnt lgkmcnt(0)
	v_mfma_f32_32x32x16_bf16 v[50:65], v[182:185], v[78:81], v[50:65]
	s_cbranch_scc1 .LBB0_360
	v_add_u32_e32 v0, s35, v102
	v_add_u32_e32 v133, 0xa0, v0
	v_add_u32_e32 v132, 0x80, v0
	v_cmp_le_i32_e32 vcc, v133, v136
	s_nop 6
	v_cndmask_b32_e32 v50, v238, v50, vcc
	v_cmp_lt_i32_e32 vcc, v132, v136
	s_nop 1
	v_cndmask_b32_e32 v35, v238, v35, vcc
	v_cmp_le_i32_e32 vcc, v132, v136
	v_add_u32_e32 v132, 0xa1, v0
	s_nop 0
	v_cndmask_b32_e32 v34, v238, v34, vcc
	v_cmp_le_i32_e32 vcc, v132, v136
	v_add_u32_e32 v132, 0x82, v0
	s_nop 0
	v_cndmask_b32_e32 v51, v238, v51, vcc
	v_cmp_le_i32_e32 vcc, v132, v136
	v_add_u32_e32 v132, 0xa2, v0
	s_nop 0
	v_cndmask_b32_e32 v36, v238, v36, vcc
	v_cmp_le_i32_e32 vcc, v132, v136
	v_add_u32_e32 v132, 0x83, v0
	s_nop 0
	v_cndmask_b32_e32 v52, v238, v52, vcc
	v_cmp_le_i32_e32 vcc, v132, v136
	v_add_u32_e32 v132, 0xa3, v0
	s_nop 0
	v_cndmask_b32_e32 v37, v238, v37, vcc
	v_cmp_le_i32_e32 vcc, v132, v136
	v_add_u32_e32 v132, 0x88, v0
	s_nop 0
	v_cndmask_b32_e32 v53, v238, v53, vcc
	v_cmp_le_i32_e32 vcc, v132, v136
	v_add_u32_e32 v132, 0xa8, v0
	s_nop 0
	v_cndmask_b32_e32 v38, v238, v38, vcc
	v_cmp_le_i32_e32 vcc, v132, v136
	v_add_u32_e32 v132, 0x89, v0
	s_nop 0
	v_cndmask_b32_e32 v54, v238, v54, vcc
	v_cmp_le_i32_e32 vcc, v132, v136
	v_add_u32_e32 v132, 0xa9, v0
	s_nop 0
	v_cndmask_b32_e32 v39, v238, v39, vcc
	v_cmp_le_i32_e32 vcc, v132, v136
	v_add_u32_e32 v132, 0x8a, v0
	s_nop 0
	v_cndmask_b32_e32 v55, v238, v55, vcc
	v_cmp_le_i32_e32 vcc, v132, v136
	v_add_u32_e32 v132, 0xaa, v0
	s_nop 0
	v_cndmask_b32_e32 v40, v238, v40, vcc
	v_cmp_le_i32_e32 vcc, v132, v136
	v_add_u32_e32 v132, 0x8b, v0
	s_nop 0
	v_cndmask_b32_e32 v56, v238, v56, vcc
	v_cmp_le_i32_e32 vcc, v132, v136
	v_add_u32_e32 v132, 0xab, v0
	s_nop 0
	v_cndmask_b32_e32 v41, v238, v41, vcc
	v_cmp_le_i32_e32 vcc, v132, v136
	v_add_u32_e32 v132, 0x90, v0
	s_nop 0
	v_cndmask_b32_e32 v57, v238, v57, vcc
	v_cmp_le_i32_e32 vcc, v132, v136
	v_add_u32_e32 v132, 0xb0, v0
	s_nop 0
	v_cndmask_b32_e32 v42, v238, v42, vcc
	v_cmp_le_i32_e32 vcc, v132, v136
	v_add_u32_e32 v132, 0x91, v0
	s_nop 0
	v_cndmask_b32_e32 v58, v238, v58, vcc
	v_cmp_le_i32_e32 vcc, v132, v136
	v_add_u32_e32 v132, 0xb1, v0
	s_nop 0
	v_cndmask_b32_e32 v43, v238, v43, vcc
	v_cmp_le_i32_e32 vcc, v132, v136
	v_add_u32_e32 v132, 0x92, v0
	s_nop 0
	v_cndmask_b32_e32 v59, v238, v59, vcc
	v_cmp_le_i32_e32 vcc, v132, v136
	v_add_u32_e32 v132, 0xb2, v0
	s_nop 0
	v_cndmask_b32_e32 v44, v238, v44, vcc
	v_cmp_le_i32_e32 vcc, v132, v136
	v_add_u32_e32 v132, 0x93, v0
	s_nop 0
	v_cndmask_b32_e32 v60, v238, v60, vcc
	v_cmp_le_i32_e32 vcc, v132, v136
	v_add_u32_e32 v132, 0xb3, v0
	s_nop 0
	v_cndmask_b32_e32 v45, v238, v45, vcc
	v_cmp_le_i32_e32 vcc, v132, v136
	v_add_u32_e32 v132, 0x98, v0
	s_nop 0
	v_cndmask_b32_e32 v61, v238, v61, vcc
	v_cmp_le_i32_e32 vcc, v132, v136
	v_add_u32_e32 v132, 0xb8, v0
	s_nop 0
	v_cndmask_b32_e32 v46, v238, v46, vcc
	v_cmp_le_i32_e32 vcc, v132, v136
	v_add_u32_e32 v132, 0x99, v0
	s_nop 0
	v_cndmask_b32_e32 v62, v238, v62, vcc
	v_cmp_le_i32_e32 vcc, v132, v136
	v_add_u32_e32 v132, 0xb9, v0
	s_nop 0
	v_cndmask_b32_e32 v47, v238, v47, vcc
	v_cmp_le_i32_e32 vcc, v132, v136
	v_add_u32_e32 v132, 0x9a, v0
	s_nop 0
	v_cndmask_b32_e32 v63, v238, v63, vcc
	v_cmp_le_i32_e32 vcc, v132, v136
	v_add_u32_e32 v132, 0xba, v0
	s_nop 0
	v_cndmask_b32_e32 v48, v238, v48, vcc
	v_cmp_le_i32_e32 vcc, v132, v136
	v_add_u32_e32 v132, 0x9b, v0
	v_add_u32_e32 v0, 0xbb, v0
	v_cndmask_b32_e32 v64, v238, v64, vcc
	v_cmp_le_i32_e32 vcc, v132, v136
	s_nop 1
	v_cndmask_b32_e32 v49, v238, v49, vcc
	v_cmp_le_i32_e32 vcc, v0, v136
	s_nop 1
	v_cndmask_b32_e32 v65, v238, v65, vcc
